# grid barrier poll keeps two counter loads in flight (half the worst-case detection delay)
# baseline (speedup 1.0000x reference)
.Lxb_wait_0:
	buffer_inv sc1
	s_mov_b32 s16, 0
	global_load_dword v254, v6, s[14:15] sc1
	s_sleep 14
.Lxb_spin_0:
	global_load_dword v255, v6, s[14:15] sc1
	s_add_u32 s16, s16, 1
	s_waitcnt vmcnt(1)
	v_cmp_ge_u32_e32 vcc, v254, v4
	s_cbranch_vccnz .Lxb_done_0
	global_load_dword v254, v6, s[14:15] sc1
	s_waitcnt vmcnt(1)
	v_cmp_ge_u32_e32 vcc, v255, v4
	s_cbranch_vccnz .Lxb_done_0
	s_cmp_lt_u32 s16, 0x200000
	s_cbranch_scc1 .Lxb_spin_0
